# defer weight bf16 conversion for layers>=1 to CUs idle during GLA scan
# speedup vs baseline: 1.0294x; 1.0294x over previous
;     ...
;     for (int i = 0; i < 32; ++i) { const int kk = 2 * i + (lane >> 5); const int k = k0 + kk, kr = perm ? ((k & ~511) | fnet_chan(k & 511)) : k;
;         scr[kk * 33 + (lane & 31)] = __builtin_nontemporal_load(W + (size_t)kr * N + n0 + (lane & 31)); }
; DI void phase_prologue(const Frame& F0, const Args& a) {
;     ...
;         const int gw = F.vcu * NWAVES + F.wave, NGW = F.G * NWAVES;
;         constexpr int I_IN = 32 * (GIN / 32), I_SQ = 32 * 64, I_GU = 32 * (2 * DFF / 32), I_DN = (DFF / 64) * 64;
;         constexpr int NITEMS = 2 * I_IN + 2 * I_SQ + 2 * I_SQ + DEPTH * I_GU + DEPTH * I_DN;
;         for (int it = gw; it < NITEMS; it += NGW) {
;             int r = it;
;             if (r < 2 * I_IN) { const int j = r / I_IN; r %= I_IN; const int nblk = GIN / 32, kb = r / nblk, nb = r % nblk;
;                 transpose_item(a.gla_w_in + (size_t)j * DM * GIN, DM, GIN, (bf16*)(ws + WS_WIN) + (size_t)j * GIN_PAD * DM, 64 * kb, 32 * nb, 32 * nb, scr, F.lane); continue; }
;             r -= 2 * I_IN;
;             if (r < 2 * I_SQ) { const int j = r / I_SQ; r %= I_SQ; const int kb = r / 64, nb = r % 64;
;                 transpose_item(a.gla_w_out + (size_t)j * DM * DM, DM, DM, (bf16*)(ws + WS_WGO) + (size_t)j * DM * DM, 64 * kb, 32 * nb, 32 * nb, scr, F.lane); continue; }
;             r -= 2 * I_SQ;
;             if (r < 2 * I_SQ) { const int j = r / I_SQ; r %= I_SQ; const int kb = r / 64, nb = r % 64;
;                 transpose_item(a.fnet_w_out + (size_t)j * DM * DM, DM, DM, (bf16*)(ws + WS_WFO) + (size_t)j * DM * DM, 64 * kb, 32 * nb, 32 * nb, scr, F.lane, 1); continue; }
;             r -= 2 * I_SQ;
;             if (r < DEPTH * I_GU) { const int j = r / I_GU; r %= I_GU; const int nblk = 2 * DFF / 32, kb = r / nblk, nb = r % nblk, n0 = 32 * nb;
;                 const int jj = n0 < DFF ? n0 : n0 - DFF; const int drow = (jj >> 7) * 256 + (n0 < DFF ? 0 : 128) + (jj & 127);
;                 transpose_item(a.ffn_w_gu + (size_t)j * DM * 2 * DFF, DM, 2 * DFF, (bf16*)(ws + WS_WGU) + (size_t)j * 2 * DFF * DM, 64 * kb, n0, drow, scr, F.lane); continue; }
;             r -= DEPTH * I_GU;
;             { const int j = r / I_DN; r %= I_DN; const int kb = r / 64, nb = r % 64;
;                 transpose_item(a.ffn_w_down + (size_t)j * DFF * DM, DFF, DM, (bf16*)(ws + WS_WDN) + (size_t)j * DM * DFF, 64 * kb, 32 * nb, 32 * nb, scr, F.lane); }
.LBB0_79:
	s_or_b64 exec, exec, s[8:9]
	s_lshl_b32 s0, s60, 3
	s_add_i32 s6, s0, s44
	s_cmp_gt_i32 s6, 0x1583f
	s_cbranch_scc1 .LBB0_11
	s_mov_b32 s90, s6
	s_mov_b32 s92, 0
	s_mov_b32 s91, 0x15840
	v_readlane_b32 s93, v252, 53
	s_cmp_eq_u32 s3, 0x100
	s_cbranch_scc0 .Lconv_entry
	s_mov_b32 s92, 1
	s_mov_b32 s91, 0x6220
.Lconv_entry:
	s_mul_i32 s16, s44, 0x2100
	s_add_i32 s0, s16, 0
	s_add_u32 s7, s86, 0x102a0000
	s_addc_u32 s8, s87, 0
	s_add_u32 s9, s86, 0x52a0000
	s_addc_u32 s10, s87, 0
	s_add_u32 s11, s86, 0x42a0000
	s_addc_u32 s12, s87, 0
	v_lshlrev_b32_e32 v4, 3, v78
	s_add_u32 s13, s86, 0x32a0000
	v_ashrrev_i32_e32 v1, 5, v78
	s_movk_i32 s1, 0x84
	v_ashrrev_i32_e32 v44, 3, v78
	v_and_b32_e32 v4, 56, v4
	s_addc_u32 s14, s87, 0
	v_and_b32_e32 v2, 31, v78
	v_mul_lo_u32 v5, v1, s1
	v_mul_u32_u24_e32 v6, 0x84, v4
	v_lshlrev_b32_e32 v7, 2, v44
	s_add_u32 s15, s86, 0xa0000
	s_mov_b32 s86, s93
	v_lshl_add_u32 v3, v2, 2, s0
	v_add_u32_e32 v8, 2, v1
	v_add_u32_e32 v9, 4, v1
	v_add_u32_e32 v10, 6, v1
	v_add_u32_e32 v11, 8, v1
	v_add_u32_e32 v12, 10, v1
	v_add_u32_e32 v13, 0x528, v5
	v_add_u32_e32 v14, 12, v1
	v_add_u32_e32 v15, 14, v1
	v_add_u32_e32 v16, 16, v1
	v_add_u32_e32 v17, 18, v1
	v_add_u32_e32 v18, 20, v1
	v_add_u32_e32 v19, 0xa50, v5
	v_add_u32_e32 v20, 22, v1
	v_add_u32_e32 v21, 24, v1
	v_add_u32_e32 v22, 26, v1
	v_add_u32_e32 v23, 28, v1
	v_add_u32_e32 v24, 30, v1
	v_add_u32_e32 v25, 0xf78, v5
	v_add_u32_e32 v26, 32, v1
	v_add_u32_e32 v27, 34, v1
	v_add_u32_e32 v28, 36, v1
	v_add_u32_e32 v29, 38, v1
	v_add_u32_e32 v30, 40, v1
	v_add_u32_e32 v31, 0x14a0, v5
	v_add_u32_e32 v32, 42, v1
	v_add_u32_e32 v33, 44, v1
	v_add_u32_e32 v34, 46, v1
	v_add_u32_e32 v35, 48, v1
	v_add_u32_e32 v36, 50, v1
	v_add_u32_e32 v37, 0x19c8, v5
	v_add_u32_e32 v38, 52, v1
	v_add_u32_e32 v39, 54, v1
	v_add_u32_e32 v40, 56, v1
	v_add_u32_e32 v41, 58, v1
	v_add_u32_e32 v42, 60, v1
	v_add_u32_e32 v43, 62, v1
	v_add3_u32 v45, s0, v6, v7
	v_add_u32_e32 v46, 8, v44
	v_add_u32_e32 v47, 16, v44
	v_add_u32_e32 v48, 24, v44
	s_addc_u32 s60, s87, 0
	s_lshl_b32 s61, s6, 5
	s_lshl_b32 s62, s86, 5
	s_branch .LBB0_82
.LBB0_81:
	s_add_i32 s90, s90, s86
	s_cmp_lt_i32 s90, s91
	s_cbranch_scc0 .Lconv_exit
.LBB0_82:
	s_cmp_eq_u32 s92, 0
	s_cbranch_scc1 .Lconv_map0
	s_cmp_eq_u32 s92, 1
	s_cbranch_scc1 .Lconv_map1
	s_cmp_eq_u32 s92, 2
	s_cbranch_scc1 .Lconv_map2
	s_mov_b32 s0, 0xcc40
	s_cmp_lt_i32 s90, 0x6000
	s_cselect_b32 s0, 0xa040, s0
	s_cmp_lt_i32 s90, 0x800
	s_cselect_b32 s0, 0x4840, s0
	s_add_i32 s6, s90, s0
	s_branch .Lconv_mapped
.Lconv_map2:
	s_mov_b32 s0, 0xc220
	s_cmp_lt_i32 s90, 0x5420
	s_cselect_b32 s0, 0x5420, s0
	s_cmp_lt_i32 s90, 0x2820
	s_cselect_b32 s0, 0x2020, s0
	s_cmp_lt_i32 s90, 0x1820
	s_cselect_b32 s0, 0x1820, s0
	s_add_i32 s6, s90, s0
	s_branch .Lconv_mapped
.Lconv_map1:
	s_mov_b32 s0, 0xb420
	s_cmp_lt_i32 s90, 0x4c20
	s_cselect_b32 s0, 0x3020, s0
	s_cmp_lt_i32 s90, 0x2020
	s_cselect_b32 s0, 0x1820, s0
	s_cmp_lt_i32 s90, 0x1820
	s_cselect_b32 s0, 0x0, s0
	s_add_i32 s6, s90, s0
	s_branch .Lconv_mapped
.Lconv_map0:
	s_mov_b32 s6, s90
.Lconv_mapped:
	s_lshl_b32 s61, s6, 5
	s_cmpk_gt_i32 s6, 0x303f
	s_mov_b64 s[0:1], -1
	s_cbranch_scc0 .LBB0_96
	s_cmpk_gt_u32 s6, 0x403f
	s_cbranch_scc0 .LBB0_93
	s_cmpk_gt_u32 s6, 0x503f
	s_cbranch_scc0 .LBB0_90
	s_cmp_gt_u32 s6, 0x1003f
	s_cbranch_scc0 .LBB0_87
	s_add_i32 s0, s6, 0xffc0
	s_and_b32 s1, s0, 0xffff
	s_mul_i32 s1, s1, 0xba2f
	s_lshr_b32 s4, s1, 28
	s_mul_i32 s1, s4, 0x1600
	s_sub_i32 s0, s0, s1
	s_and_b32 s16, s0, 0xffff
	s_and_b32 s1, s0, 0x1fc0
	s_mul_i32 s0, s4, 0x2c00000
	v_readlane_b32 s80, v252, 0
	v_readlane_b32 s81, v252, 1
	s_add_u32 s63, s80, s0
	s_addc_u32 s81, s81, 0
	s_mul_i32 s4, s4, 0x1600000
	s_add_u32 s4, s7, s4
	s_addc_u32 s5, s8, 0
	s_lshl_b32 s0, s16, 5
	s_and_b32 s0, s0, 0x7e0
	s_lshl_b32 s16, s0, 2
	s_add_u32 s80, s63, s16
	v_add_u32_e32 v50, s1, v1
	v_add_u32_e32 v52, s1, v8
	v_add_u32_e32 v56, s1, v9
	v_add_u32_e32 v58, s1, v10
	v_add_u32_e32 v60, s1, v11
	v_add_u32_e32 v62, s1, v12
	v_add_u32_e32 v64, s1, v14
	v_add_u32_e32 v66, s1, v15
	s_addc_u32 s81, s81, 0
	v_lshlrev_b32_e32 v54, 2, v2
	v_ashrrev_i32_e32 v51, 31, v50
	v_ashrrev_i32_e32 v53, 31, v52
	v_ashrrev_i32_e32 v57, 31, v56
	v_ashrrev_i32_e32 v59, 31, v58
	v_ashrrev_i32_e32 v61, 31, v60
	v_ashrrev_i32_e32 v63, 31, v62
	v_ashrrev_i32_e32 v65, 31, v64
	v_ashrrev_i32_e32 v67, 31, v66
	v_lshl_add_u64 v[6:7], s[80:81], 0, v[54:55]
	v_lshlrev_b64 v[50:51], 13, v[50:51]
	v_lshlrev_b64 v[52:53], 13, v[52:53]
	v_lshlrev_b64 v[56:57], 13, v[56:57]
	v_lshlrev_b64 v[58:59], 13, v[58:59]
	v_lshlrev_b64 v[60:61], 13, v[60:61]
	v_lshlrev_b64 v[62:63], 13, v[62:63]
	v_lshlrev_b64 v[64:65], 13, v[64:65]
	v_lshlrev_b64 v[66:67], 13, v[66:67]
	v_lshl_add_u64 v[50:51], v[6:7], 0, v[50:51]
	v_lshl_add_u64 v[52:53], v[6:7], 0, v[52:53]
	v_lshl_add_u64 v[56:57], v[6:7], 0, v[56:57]
	v_lshl_add_u64 v[58:59], v[6:7], 0, v[58:59]
	v_lshl_add_u64 v[60:61], v[6:7], 0, v[60:61]
	v_lshl_add_u64 v[62:63], v[6:7], 0, v[62:63]
	v_lshl_add_u64 v[64:65], v[6:7], 0, v[64:65]
	v_lshl_add_u64 v[66:67], v[6:7], 0, v[66:67]
	global_load_dword v49, v[50:51], off nt
	global_load_dword v54, v[52:53], off nt
	global_load_dword v68, v[56:57], off nt
	global_load_dword v69, v[58:59], off nt
	global_load_dword v70, v[60:61], off nt
	global_load_dword v71, v[62:63], off nt
	global_load_dword v78, v[64:65], off nt
	global_load_dword v79, v[66:67], off nt
	v_add_u32_e32 v50, s1, v16
	v_add_u32_e32 v52, s1, v17
	v_add_u32_e32 v56, s1, v18
	v_add_u32_e32 v58, s1, v20
	v_add_u32_e32 v60, s1, v21
	v_add_u32_e32 v62, s1, v22
	v_add_u32_e32 v64, s1, v23
	v_add_u32_e32 v66, s1, v24
;     ...
;     for (int i = 0; i < 32; ++i) { const int kk = 2 * i + (lane >> 5); const int k = k0 + kk, kr = perm ? ((k & ~511) | fnet_chan(k & 511)) : k;
;         scr[kk * 33 + (lane & 31)] = __builtin_nontemporal_load(W + (size_t)kr * N + n0 + (lane & 31)); }
	v_ashrrev_i32_e32 v51, 31, v50
	v_ashrrev_i32_e32 v53, 31, v52
	v_ashrrev_i32_e32 v57, 31, v56
	v_ashrrev_i32_e32 v59, 31, v58
	v_ashrrev_i32_e32 v61, 31, v60
	v_ashrrev_i32_e32 v63, 31, v62
	v_ashrrev_i32_e32 v65, 31, v64
	v_ashrrev_i32_e32 v67, 31, v66
	v_lshlrev_b64 v[50:51], 13, v[50:51]
	v_lshlrev_b64 v[52:53], 13, v[52:53]
	v_lshlrev_b64 v[56:57], 13, v[56:57]
	v_lshlrev_b64 v[58:59], 13, v[58:59]
	v_lshlrev_b64 v[60:61], 13, v[60:61]
	v_lshlrev_b64 v[62:63], 13, v[62:63]
	v_lshlrev_b64 v[64:65], 13, v[64:65]
	v_lshlrev_b64 v[66:67], 13, v[66:67]
	v_lshl_add_u64 v[50:51], v[6:7], 0, v[50:51]
	v_lshl_add_u64 v[52:53], v[6:7], 0, v[52:53]
	v_lshl_add_u64 v[56:57], v[6:7], 0, v[56:57]
	v_lshl_add_u64 v[58:59], v[6:7], 0, v[58:59]
	v_lshl_add_u64 v[60:61], v[6:7], 0, v[60:61]
	v_lshl_add_u64 v[62:63], v[6:7], 0, v[62:63]
	v_lshl_add_u64 v[64:65], v[6:7], 0, v[64:65]
	v_lshl_add_u64 v[66:67], v[6:7], 0, v[66:67]
	global_load_dword v80, v[50:51], off nt
	global_load_dword v81, v[52:53], off nt
	global_load_dword v82, v[56:57], off nt
	global_load_dword v83, v[58:59], off nt
	global_load_dword v84, v[60:61], off nt
	global_load_dword v85, v[62:63], off nt
	global_load_dword v86, v[64:65], off nt
	global_load_dword v87, v[66:67], off nt
	v_add_u32_e32 v50, s1, v26
	v_add_u32_e32 v52, s1, v27
	v_add_u32_e32 v56, s1, v28
	v_add_u32_e32 v58, s1, v29
	v_add_u32_e32 v60, s1, v30
	v_add_u32_e32 v62, s1, v32
	v_add_u32_e32 v64, s1, v33
	v_add_u32_e32 v66, s1, v34
	v_ashrrev_i32_e32 v51, 31, v50
	v_ashrrev_i32_e32 v53, 31, v52
	v_ashrrev_i32_e32 v57, 31, v56
	v_ashrrev_i32_e32 v59, 31, v58
	v_ashrrev_i32_e32 v61, 31, v60
	v_ashrrev_i32_e32 v63, 31, v62
	v_ashrrev_i32_e32 v65, 31, v64
	v_ashrrev_i32_e32 v67, 31, v66
	v_lshlrev_b64 v[50:51], 13, v[50:51]
	v_lshlrev_b64 v[52:53], 13, v[52:53]
	v_lshlrev_b64 v[56:57], 13, v[56:57]
	v_lshlrev_b64 v[58:59], 13, v[58:59]
	v_lshlrev_b64 v[60:61], 13, v[60:61]
	v_lshlrev_b64 v[62:63], 13, v[62:63]
	v_lshlrev_b64 v[64:65], 13, v[64:65]
	v_lshlrev_b64 v[66:67], 13, v[66:67]
	v_lshl_add_u64 v[50:51], v[6:7], 0, v[50:51]
	v_lshl_add_u64 v[52:53], v[6:7], 0, v[52:53]
	v_lshl_add_u64 v[56:57], v[6:7], 0, v[56:57]
	v_lshl_add_u64 v[58:59], v[6:7], 0, v[58:59]
	v_lshl_add_u64 v[60:61], v[6:7], 0, v[60:61]
	v_lshl_add_u64 v[62:63], v[6:7], 0, v[62:63]
	v_lshl_add_u64 v[64:65], v[6:7], 0, v[64:65]
	v_lshl_add_u64 v[66:67], v[6:7], 0, v[66:67]
	global_load_dword v88, v[50:51], off nt
	global_load_dword v89, v[52:53], off nt
	global_load_dword v90, v[56:57], off nt
	global_load_dword v91, v[58:59], off nt
	global_load_dword v92, v[60:61], off nt
	global_load_dword v93, v[62:63], off nt
	global_load_dword v94, v[64:65], off nt
	global_load_dword v95, v[66:67], off nt
	v_add_u32_e32 v50, s1, v35
	v_add_u32_e32 v52, s1, v36
	v_add_u32_e32 v56, s1, v38
	v_add_u32_e32 v58, s1, v39
	v_add_u32_e32 v60, s1, v40
	v_add_u32_e32 v62, s1, v41
	v_add_u32_e32 v64, s1, v42
	v_add_u32_e32 v66, s1, v43
	v_ashrrev_i32_e32 v51, 31, v50
	v_ashrrev_i32_e32 v53, 31, v52
	v_ashrrev_i32_e32 v57, 31, v56
	v_ashrrev_i32_e32 v59, 31, v58
	v_ashrrev_i32_e32 v61, 31, v60
	v_ashrrev_i32_e32 v63, 31, v62
	v_ashrrev_i32_e32 v65, 31, v64
	v_ashrrev_i32_e32 v67, 31, v66
	v_lshlrev_b64 v[50:51], 13, v[50:51]
	v_lshlrev_b64 v[52:53], 13, v[52:53]
	v_lshlrev_b64 v[56:57], 13, v[56:57]
	v_lshlrev_b64 v[58:59], 13, v[58:59]
	v_lshlrev_b64 v[60:61], 13, v[60:61]
	v_lshlrev_b64 v[62:63], 13, v[62:63]
	v_lshlrev_b64 v[64:65], 13, v[64:65]
	v_lshlrev_b64 v[66:67], 13, v[66:67]
	v_lshl_add_u64 v[50:51], v[6:7], 0, v[50:51]
	v_lshl_add_u64 v[52:53], v[6:7], 0, v[52:53]
	v_lshl_add_u64 v[56:57], v[6:7], 0, v[56:57]
	v_lshl_add_u64 v[58:59], v[6:7], 0, v[58:59]
	v_lshl_add_u64 v[60:61], v[6:7], 0, v[60:61]
	v_lshl_add_u64 v[62:63], v[6:7], 0, v[62:63]
	v_lshl_add_u64 v[64:65], v[6:7], 0, v[64:65]
	v_lshl_add_u64 v[6:7], v[6:7], 0, v[66:67]
	global_load_dword v50, v[50:51], off nt
	s_nop 0
	global_load_dword v51, v[52:53], off nt
	s_nop 0
	global_load_dword v52, v[56:57], off nt
	global_load_dword v53, v[58:59], off nt
	s_nop 0
	global_load_dword v56, v[60:61], off nt
	global_load_dword v57, v[62:63], off nt
	global_load_dword v58, v[64:65], off nt
	s_nop 0
	global_load_dword v6, v[6:7], off nt
	v_add_u32_e32 v7, v3, v5
	v_add_u32_e32 v59, 0xa800, v7
	s_waitcnt vmcnt(30)
; #define GAS __attribute__((address_space(1)))
; #define LAS __attribute__((address_space(3)))
; #define LDS_WAIT() asm volatile("s_waitcnt lgkmcnt(0)" ::: "memory")
; DI unsigned pk2(float lo, float hi) { f32x2_t v = {lo, hi}; bf16x2_t b = __builtin_convertvector(v, bf16x2_t); return __builtin_bit_cast(unsigned, b); }
;     ...
;     for (int i = 0; i < 32; ++i) { const int kk = 2 * i + (lane >> 5); const int k = k0 + kk, kr = perm ? ((k & ~511) | fnet_chan(k & 511)) : k;
;         scr[kk * 33 + (lane & 31)] = __builtin_nontemporal_load(W + (size_t)kr * N + n0 + (lane & 31)); }
;     LDS_WAIT(); asm volatile("" ::: "memory");
;     const int c = lane & 7;
; #pragma unroll
;     for (int j = 0; j < 4; ++j) { const int n = (lane >> 3) + 8 * j; const LAS float* s = scr + (8 * c) * 33 + n;
;         v4u o; o.x = pk2(s[0 * 33], s[1 * 33]); o.y = pk2(s[2 * 33], s[3 * 33]); o.z = pk2(s[4 * 33], s[5 * 33]); o.w = pk2(s[6 * 33], s[7 * 33]);
;         __builtin_nontemporal_store(o, (GAS v4u*)(WT + (size_t)(drow0 + n) * K + k0 + 8 * c)); }
;     LDS_WAIT(); asm volatile("" ::: "memory");
	ds_write2_b32 v59, v49, v54 offset1:66
	s_waitcnt vmcnt(28)
	ds_write2_b32 v59, v68, v69 offset0:132 offset1:198
	s_waitcnt vmcnt(27)
	ds_write_b32 v7, v70 offset:44064
	v_add_u32_e32 v7, v3, v13
	v_add_u32_e32 v49, 0xa800, v7
	s_waitcnt vmcnt(25)
	ds_write2_b32 v49, v71, v78 offset1:66
	s_waitcnt vmcnt(23)
	ds_write2_b32 v49, v79, v80 offset0:132 offset1:198
	s_waitcnt vmcnt(22)
	ds_write_b32 v7, v81 offset:44064
	v_add_u32_e32 v7, v3, v19
	v_add_u32_e32 v49, 0xa800, v7
	s_waitcnt vmcnt(20)
	ds_write2_b32 v49, v82, v83 offset1:66
	s_waitcnt vmcnt(18)
	ds_write2_b32 v49, v84, v85 offset0:132 offset1:198
	s_waitcnt vmcnt(17)
	ds_write_b32 v7, v86 offset:44064
	v_add_u32_e32 v7, v3, v25
	v_add_u32_e32 v49, 0xa800, v7
	s_waitcnt vmcnt(15)
	ds_write2_b32 v49, v87, v88 offset1:66
	s_waitcnt vmcnt(13)
	ds_write2_b32 v49, v89, v90 offset0:132 offset1:198
	s_waitcnt vmcnt(12)
	ds_write_b32 v7, v91 offset:44064
	v_add_u32_e32 v7, v3, v31
	v_add_u32_e32 v49, 0xa800, v7
	s_waitcnt vmcnt(10)
	ds_write2_b32 v49, v92, v93 offset1:66
	s_waitcnt vmcnt(8)
	ds_write2_b32 v49, v94, v95 offset0:132 offset1:198
	s_waitcnt vmcnt(7)
	ds_write_b32 v7, v50 offset:44064
	v_add_u32_e32 v7, v3, v37
	v_add_u32_e32 v49, 0xa800, v7
	s_waitcnt vmcnt(5)
	ds_write2_b32 v49, v51, v52 offset1:66
	s_waitcnt vmcnt(3)
	ds_write2_b32 v49, v53, v56 offset0:132 offset1:198
	v_add_u32_e32 v49, 0xac00, v7
	s_waitcnt vmcnt(1)
	ds_write2_b32 v49, v57, v58 offset0:8 offset1:74
	s_waitcnt vmcnt(0)
	ds_write_b32 v7, v6 offset:44592
	s_waitcnt lgkmcnt(0)
	v_add_u32_e32 v49, 0xa800, v45
	ds_read2_b32 v[6:7], v49 offset0:33 offset1:41
	ds_read2_b32 v[56:57], v49 offset1:8
	ds_read2_b32 v[58:59], v49 offset0:66 offset1:74
	ds_read2_b32 v[60:61], v49 offset0:99 offset1:107
	ds_read2_b32 v[62:63], v49 offset0:132 offset1:140
	ds_read2_b32 v[64:65], v49 offset0:165 offset1:173
	ds_read2_b32 v[66:67], v49 offset0:198 offset1:206
	ds_read2_b32 v[68:69], v49 offset0:231 offset1:239
	s_lshl_b32 s1, s1, 1
	s_add_u32 s4, s4, s1
	s_addc_u32 s5, s5, 0
	v_lshlrev_b32_e32 v54, 1, v4
	v_lshl_add_u64 v[70:71], s[4:5], 0, v[54:55]
	s_waitcnt lgkmcnt(6)
	v_cvt_pk_bf16_f32 v50, v56, v6
	v_add_u32_e32 v6, s0, v44
	s_movk_i32 s1, 0x2c00
	s_waitcnt lgkmcnt(4)
	v_cvt_pk_bf16_f32 v51, v58, v60
	s_waitcnt lgkmcnt(2)
	v_cvt_pk_bf16_f32 v52, v62, v64
	s_waitcnt lgkmcnt(0)
	v_cvt_pk_bf16_f32 v53, v66, v68
	v_mad_i64_i32 v[78:79], s[4:5], v6, s1, v[70:71]
	global_store_dwordx4 v[78:79], v[50:53], off nt
	v_add_u32_e32 v6, s0, v46
	v_readlane_b32 s82, v252, 2
	v_cvt_pk_bf16_f32 v50, v57, v7
	v_cvt_pk_bf16_f32 v51, v59, v61
	v_cvt_pk_bf16_f32 v52, v63, v65
	v_cvt_pk_bf16_f32 v53, v67, v69
	ds_read2_b32 v[56:57], v49 offset0:49 offset1:57
	ds_read2_b32 v[58:59], v49 offset0:16 offset1:24
	ds_read2_b32 v[60:61], v49 offset0:82 offset1:90
	ds_read2_b32 v[62:63], v49 offset0:115 offset1:123
	ds_read2_b32 v[64:65], v49 offset0:148 offset1:156
	ds_read2_b32 v[66:67], v49 offset0:181 offset1:189
	ds_read2_b32 v[68:69], v49 offset0:214 offset1:222
	ds_read2_b32 v[78:79], v49 offset0:247 offset1:255
	v_mad_i64_i32 v[6:7], s[4:5], v6, s1, v[70:71]
	global_store_dwordx4 v[6:7], v[50:53], off nt
	v_add_u32_e32 v6, s0, v47
	v_mad_i64_i32 v[6:7], s[4:5], v6, s1, v[70:71]
	s_waitcnt lgkmcnt(6)
	v_cvt_pk_bf16_f32 v50, v58, v56
	s_waitcnt lgkmcnt(4)
	v_cvt_pk_bf16_f32 v51, v60, v62
	s_waitcnt lgkmcnt(2)
	v_cvt_pk_bf16_f32 v52, v64, v66
	s_waitcnt lgkmcnt(0)
	v_cvt_pk_bf16_f32 v53, v68, v78
	global_store_dwordx4 v[6:7], v[50:53], off nt
	v_add_u32_e32 v6, s0, v48
	v_mad_i64_i32 v[6:7], s[0:1], v6, s1, v[70:71]
	v_cvt_pk_bf16_f32 v50, v59, v57
	v_cvt_pk_bf16_f32 v51, v61, v63
	v_cvt_pk_bf16_f32 v52, v65, v67
	v_cvt_pk_bf16_f32 v53, v69, v79
	global_store_dwordx4 v[6:7], v[50:53], off nt
	s_waitcnt lgkmcnt(0)
	v_readlane_b32 s83, v252, 3
	s_mov_b64 s[0:1], 0

; DI void phase_prologue(const Frame& F0, const Args& a) {
;     ...
;         const int gw = F.vcu * NWAVES + F.wave, NGW = F.G * NWAVES;
;         constexpr int I_IN = 32 * (GIN / 32), I_SQ = 32 * 64, I_GU = 32 * (2 * DFF / 32), I_DN = (DFF / 64) * 64;
;         constexpr int NITEMS = 2 * I_IN + 2 * I_SQ + 2 * I_SQ + DEPTH * I_GU + DEPTH * I_DN;
;         for (int it = gw; it < NITEMS; it += NGW) {
; DI void phase_scan(const Frame& F0, const Args& a, int colmajor) {
;     ...
;     for (int it = F.vcu; it < 256; it += F.G) {
;         if ((it & 31) >= 16) continue;
.Lconv_exit:
	s_cmp_gt_u32 s92, 1
	s_cbranch_scc1 .Lconv_ret_scan
	s_branch .LBB0_10
.Lconv_scan_idle:
	s_cmp_eq_u32 s3, 0x100
	s_cbranch_scc0 .LBB0_821
	v_writelane_b32 v100, s11, 0
	v_writelane_b32 v100, s20, 1
	v_writelane_b32 v100, s21, 2
	v_writelane_b32 v100, s22, 3
	v_writelane_b32 v100, s26, 4
	v_writelane_b32 v100, s28, 5
	v_writelane_b32 v100, s29, 6
	v_writelane_b32 v100, s30, 7
	v_writelane_b32 v100, s31, 8
	v_writelane_b32 v100, s44, 9
	v_writelane_b32 v100, s45, 10
	v_writelane_b32 v100, s48, 11
	v_writelane_b32 v100, s49, 12
	v_writelane_b32 v100, s50, 13
	v_writelane_b32 v100, s51, 14
	v_writelane_b32 v100, s52, 15
	v_writelane_b32 v100, s53, 16
	v_writelane_b32 v100, s54, 17
	v_writelane_b32 v100, s55, 18
	v_writelane_b32 v100, s57, 19
	v_writelane_b32 v100, s58, 20
	v_writelane_b32 v100, s59, 21
	v_writelane_b32 v100, s64, 22
	v_writelane_b32 v100, s73, 23
	v_writelane_b32 v100, s80, 24
	v_writelane_b32 v100, s81, 25
	v_writelane_b32 v100, s83, 26
	v_writelane_b32 v100, s86, 27
	v_writelane_b32 v100, s87, 28
	v_mov_b32_e32 v101, v1
	v_mov_b32_e32 v102, v3
	v_readlane_b32 s0, v255, 17
	v_readlane_b32 s1, v252, 48
	v_readlane_b32 s44, v252, 49
	v_readlane_b32 s86, v252, 46
	v_readlane_b32 s87, v252, 47
	s_movk_i32 s34, 0xfe00
	s_mov_b32 s65, 0
	s_movk_i32 s70, 0x101
	s_movk_i32 s73, 0x6080
	v_mov_b32_e32 v55, 0
	v_mov_b32_e32 v78, v222
	s_lshr_b32 s4, s1, 5
	s_lshl_b32 s4, s4, 4
	s_and_b32 s5, s1, 15
	s_or_b32 s4, s4, s5
	s_lshl_b32 s4, s4, 3
	s_add_i32 s90, s4, s44
	s_movk_i32 s93, 0x400
	s_mov_b32 s4, 0x6a20
	s_mov_b32 s5, 0x8c00
	s_cmp_eq_u32 s0, 0
	s_cselect_b32 s92, 2, 3
	s_cselect_b32 s91, s4, s5
	s_mov_b32 s6, s90
	s_cmp_lt_i32 s90, s91
	s_cbranch_scc1 .Lconv_entry
.Lconv_ret_scan:
	s_waitcnt vmcnt(0) lgkmcnt(0)
	v_readlane_b32 s11, v100, 0
	v_readlane_b32 s20, v100, 1
	v_readlane_b32 s21, v100, 2
	v_readlane_b32 s22, v100, 3
	v_readlane_b32 s26, v100, 4
	v_readlane_b32 s28, v100, 5
	v_readlane_b32 s29, v100, 6
	v_readlane_b32 s30, v100, 7
	v_readlane_b32 s31, v100, 8
	v_readlane_b32 s44, v100, 9
	v_readlane_b32 s45, v100, 10
	v_readlane_b32 s48, v100, 11
	v_readlane_b32 s49, v100, 12
	v_readlane_b32 s50, v100, 13
	v_readlane_b32 s51, v100, 14
	v_readlane_b32 s52, v100, 15
	v_readlane_b32 s53, v100, 16
	v_readlane_b32 s54, v100, 17
	v_readlane_b32 s55, v100, 18
	v_readlane_b32 s57, v100, 19
	v_readlane_b32 s58, v100, 20
	v_readlane_b32 s59, v100, 21
	v_readlane_b32 s64, v100, 22
	v_readlane_b32 s73, v100, 23
	v_readlane_b32 s80, v100, 24
	v_readlane_b32 s81, v100, 25
	v_readlane_b32 s83, v100, 26
	v_readlane_b32 s86, v100, 27
	v_readlane_b32 s87, v100, 28
	v_mov_b32_e32 v1, v101
	v_mov_b32_e32 v3, v102
	s_nop 4
	s_branch .LBB0_821
